# deferred weight transposes run inside the layer-0 in-projection tile loop instead (XCD x before tile x%5), none in mixer pass 1
# baseline (speedup 1.0000x reference)
.LBB0_221:
	s_sub_u32 s0, s87, s86
	s_and_b32 s1, s86, 7
	s_sub_u32 s16, s1, 5
	s_cmp_ge_u32 s1, 5
	s_cselect_b32 s1, s16, s1
	s_mul_i32 s1, s1, s84
	s_cmp_lg_u32 s0, s1
	s_cbranch_scc1 .Ldt2_skip
	s_mov_b32 s52, s86
	s_cmpk_lg_u32 s84, 0x100
	s_cbranch_scc1 .Ldt2_nrot
	s_xor_b32 s52, s52, 0x80
.Ldt2_nrot:
	s_addk_i32 s52, 0xa08
	s_movk_i32 s32, 0x1c10
	s_cmp_ge_u32 s52, s32
	s_cbranch_scc1 .Ldt2_skip
	s_waitcnt lgkmcnt(0)
	s_barrier
	v_readlane_b32 s54, v254, 54
	v_readlane_b32 s55, v254, 55
	v_readlane_b32 s56, v253, 2
	v_readlane_b32 s57, v253, 3
	v_readlane_b32 s58, v253, 8
	v_readlane_b32 s59, v253, 9
	v_readlane_b32 s60, v253, 10
	v_readlane_b32 s61, v253, 11
	v_readlane_b32 s62, v254, 12
	v_readlane_b32 s63, v254, 13
	v_and_b32_e32 v106, 7, v180
	v_lshrrev_b32_e32 v93, 3, v180
	s_add_u32 s54, s54, 0xa080000
	s_addc_u32 s55, s55, 0
	s_add_u32 s58, s58, 0x5000000
	s_addc_u32 s59, s59, 0
	s_add_u32 s60, s60, 0x40000
	s_addc_u32 s61, s61, 0
	v_lshlrev_b32_e32 v94, 4, v106
	v_bfe_u32 v107, v180, 3, 1
	v_lshlrev_b32_e32 v108, 2, v106
	v_lshl_add_u32 v108, v107, 1, v108
	v_mul_u32_u24_e32 v84, 0x410, v108
	v_lshrrev_b32_e32 v109, 3, v93
	v_xor_b32_e32 v109, v109, v106
	v_lshlrev_b32_e32 v109, 3, v109
	v_and_b32_e32 v110, 6, v93
	v_or_b32_e32 v109, v109, v110
	v_lshl_add_u32 v84, v109, 1, v84
	v_cmp_ne_u32_e64 s[76:77], 0, v107
	v_mov_b32_e32 v104, 0x1000504
	v_mov_b32_e32 v105, 0x3020706
	v_mov_b32_e32 v111, 0x5040100
	v_mov_b32_e32 v112, 0x7060302
	v_cndmask_b32_e64 v104, v104, v111, s[76:77]
	v_cndmask_b32_e64 v105, v105, v112, s[76:77]
	v_lshrrev_b32_e32 v106, 6, v180
	v_and_b32_e32 v107, 63, v180
	v_lshrrev_b32_e32 v108, 2, v106
	v_add_u32_e32 v109, 0, v108
	v_xor_b32_e32 v109, v109, v107
	v_lshlrev_b32_e32 v109, 4, v109
	v_add_u32_e32 v110, 0, v106
	v_mul_u32_u24_e32 v110, 0x410, v110
	v_add_u32_e32 v85, v109, v110
	v_add_u32_e32 v109, 2, v108
	v_xor_b32_e32 v109, v109, v107
	v_lshlrev_b32_e32 v109, 4, v109
	v_add_u32_e32 v110, 8, v106
	v_mul_u32_u24_e32 v110, 0x410, v110
	v_add_u32_e32 v86, v109, v110
	v_add_u32_e32 v109, 4, v108
	v_xor_b32_e32 v109, v109, v107
	v_lshlrev_b32_e32 v109, 4, v109
	v_add_u32_e32 v110, 16, v106
	v_mul_u32_u24_e32 v110, 0x410, v110
	v_add_u32_e32 v87, v109, v110
	v_add_u32_e32 v109, 6, v108
	v_xor_b32_e32 v109, v109, v107
	v_lshlrev_b32_e32 v109, 4, v109
	v_add_u32_e32 v110, 24, v106
	v_mul_u32_u24_e32 v110, 0x410, v110
	v_add_u32_e32 v88, v109, v110
	v_lshlrev_b32_e32 v109, 13, v106
	v_lshl_add_u32 v89, v107, 4, v109
	v_add_u32_e32 v90, 0x10000, v89
	v_add_u32_e32 v91, 0x20000, v89
	v_add_u32_e32 v92, 0x30000, v89
	s_mov_b32 s53, 0
	s_mov_b32 s75, 0
	s_cmpk_ge_u32 s52, 0x1410
	s_cbranch_scc1 .Ldt2_out0
	s_sub_i32 s0, s52, 0xa08
	s_mul_i32 s1, s0, 0xcc3
	s_lshr_b32 s1, s1, 20
	s_mul_i32 s16, s1, 0x141
	s_sub_u32 s16, s0, s16
	s_lshl_b32 s17, s16, 7
	s_mul_i32 s20, s1, 0x1410000
	s_add_u32 s17, s17, s20
	s_add_u32 s64, s54, s17
	s_addc_u32 s65, s55, 0
	s_mov_b32 s25, 0xa080
	s_lshl_b32 s20, s1, 10
	s_cmpk_lt_u32 s16, 0x80
	s_cbranch_scc1 .Ldt2_wlo0
	s_cmpk_eq_u32 s16, 0x80
	s_cbranch_scc1 .Ldt2_wlr0
	s_add_i32 s16, s16, -1
.Ldt2_wlo0:
	s_lshl_b32 s21, s16, 18
	s_add_u32 s21, s21, s20
	s_add_u32 s66, s58, s21
	s_addc_u32 s67, s59, 0
	s_branch .Ldt2_ud0
.Ldt2_wlr0:
	s_add_u32 s66, s60, s20
	s_addc_u32 s67, s61, 0
	s_branch .Ldt2_ud0
.Ldt2_out0:
	s_sub_i32 s0, s52, 0x1410
	s_lshr_b32 s1, s0, 10
	s_bfe_u32 s16, s0, 0x30007
	s_and_b32 s17, s0, 0x7f
	s_lshl_b32 s20, s1, 26
	s_lshl_b32 s21, s17, 7
	s_add_u32 s20, s20, s21
	s_lshl_b32 s21, s16, 23
	s_add_u32 s20, s20, s21
	s_add_u32 s64, s56, s20
	s_addc_u32 s65, s57, 0
	s_lshl_b32 s20, s1, 25
	s_lshl_b32 s21, s17, 18
	s_add_u32 s20, s20, s21
	s_lshl_b32 s21, s16, 10
	s_add_u32 s20, s20, s21
	s_add_u32 s66, s62, s20
	s_addc_u32 s67, s63, 0
	s_movk_i32 s25, 0x4000
.Ldt2_ud0:
	v_mul_u32_u24_e32 v96, s25, v93
	s_lshl_b32 s24, s25, 6
	v_add_u32_e32 v96, v96, v94
	v_add_u32_e32 v97, s24, v96
	v_add_u32_e32 v98, s24, v97
	v_add_u32_e32 v99, s24, v98
	v_add_u32_e32 v100, s24, v99
	v_add_u32_e32 v101, s24, v100
	v_add_u32_e32 v102, s24, v101
	v_add_u32_e32 v103, s24, v102
	global_load_dwordx4 v[4:7], v96, s[64:65] nt
	global_load_dwordx4 v[8:11], v97, s[64:65] nt
	global_load_dwordx4 v[12:15], v98, s[64:65] nt
	global_load_dwordx4 v[16:19], v99, s[64:65] nt
	global_load_dwordx4 v[20:23], v100, s[64:65] nt
	global_load_dwordx4 v[24:27], v101, s[64:65] nt
	global_load_dwordx4 v[28:31], v102, s[64:65] nt
	global_load_dwordx4 v[32:35], v103, s[64:65] nt
	s_mov_b32 s74, 1
	s_add_u32 s52, s52, s84
	s_cmp_ge_u32 s52, s32
	s_cbranch_scc1 .Ldt2_procA
	s_cmpk_ge_u32 s52, 0x1410
	s_cbranch_scc1 .Ldt2_out1
	s_sub_i32 s0, s52, 0xa08
	s_mul_i32 s1, s0, 0xcc3
	s_lshr_b32 s1, s1, 20
	s_mul_i32 s16, s1, 0x141
	s_sub_u32 s16, s0, s16
	s_lshl_b32 s17, s16, 7
	s_mul_i32 s20, s1, 0x1410000
	s_add_u32 s17, s17, s20
	s_add_u32 s70, s54, s17
	s_addc_u32 s71, s55, 0
	s_mov_b32 s25, 0xa080
	s_lshl_b32 s20, s1, 10
	s_cmpk_lt_u32 s16, 0x80
	s_cbranch_scc1 .Ldt2_wlo1
	s_cmpk_eq_u32 s16, 0x80
	s_cbranch_scc1 .Ldt2_wlr1
	s_add_i32 s16, s16, -1
.Ldt2_wlo1:
	s_lshl_b32 s21, s16, 18
	s_add_u32 s21, s21, s20
	s_add_u32 s34, s58, s21
	s_addc_u32 s35, s59, 0
	s_branch .Ldt2_ud1
.Ldt2_wlr1:
	s_add_u32 s34, s60, s20
	s_addc_u32 s35, s61, 0
	s_branch .Ldt2_ud1
.Ldt2_out1:
	s_sub_i32 s0, s52, 0x1410
	s_lshr_b32 s1, s0, 10
	s_bfe_u32 s16, s0, 0x30007
	s_and_b32 s17, s0, 0x7f
	s_lshl_b32 s20, s1, 26
	s_lshl_b32 s21, s17, 7
	s_add_u32 s20, s20, s21
	s_lshl_b32 s21, s16, 23
	s_add_u32 s20, s20, s21
	s_add_u32 s70, s56, s20
	s_addc_u32 s71, s57, 0
	s_lshl_b32 s20, s1, 25
	s_lshl_b32 s21, s17, 18
	s_add_u32 s20, s20, s21
	s_lshl_b32 s21, s16, 10
	s_add_u32 s20, s20, s21
	s_add_u32 s34, s62, s20
	s_addc_u32 s35, s63, 0
	s_movk_i32 s25, 0x4000
.Ldt2_ud1:
	v_mul_u32_u24_e32 v96, s25, v93
	s_lshl_b32 s24, s25, 6
	v_add_u32_e32 v96, v96, v94
	v_add_u32_e32 v97, s24, v96
	v_add_u32_e32 v98, s24, v97
	v_add_u32_e32 v99, s24, v98
	v_add_u32_e32 v100, s24, v99
	v_add_u32_e32 v101, s24, v100
	v_add_u32_e32 v102, s24, v101
	v_add_u32_e32 v103, s24, v102
	global_load_dwordx4 v[36:39], v96, s[70:71] nt
	global_load_dwordx4 v[40:43], v97, s[70:71] nt
	global_load_dwordx4 v[44:47], v98, s[70:71] nt
	global_load_dwordx4 v[48:51], v99, s[70:71] nt
	global_load_dwordx4 v[52:55], v100, s[70:71] nt
	global_load_dwordx4 v[56:59], v101, s[70:71] nt
	global_load_dwordx4 v[60:63], v102, s[70:71] nt
	global_load_dwordx4 v[64:67], v103, s[70:71] nt
	s_mov_b32 s75, 1
	s_add_u32 s52, s52, s84
.Ldt2_procA:
	s_cmp_eq_u32 s75, 0
	s_cbranch_scc1 .Ldt2_w0A
	s_cmp_lt_u32 s53, 2
	s_cbranch_scc1 .Ldt2_wsA
	s_waitcnt vmcnt(16)
	s_branch .Ldt2_wdA

.Ldt2_wdA:
	v_cvt_pk_bf16_f32 v4, v4, v5
	v_cvt_pk_bf16_f32 v6, v6, v7
	v_cvt_pk_bf16_f32 v8, v8, v9
	v_cvt_pk_bf16_f32 v10, v10, v11
	v_cvt_pk_bf16_f32 v12, v12, v13
	v_cvt_pk_bf16_f32 v14, v14, v15
	v_cvt_pk_bf16_f32 v16, v16, v17
	v_cvt_pk_bf16_f32 v18, v18, v19
	v_cvt_pk_bf16_f32 v20, v20, v21
	v_cvt_pk_bf16_f32 v22, v22, v23
	v_cvt_pk_bf16_f32 v24, v24, v25
	v_cvt_pk_bf16_f32 v26, v26, v27
	v_cvt_pk_bf16_f32 v28, v28, v29
	v_cvt_pk_bf16_f32 v30, v30, v31
	v_cvt_pk_bf16_f32 v32, v32, v33
	v_cvt_pk_bf16_f32 v34, v34, v35
	v_cndmask_b32_e64 v5, v6, v4, s[76:77]
	v_cndmask_b32_e64 v7, v4, v6, s[76:77]
	v_cndmask_b32_e64 v9, v10, v8, s[76:77]
	v_cndmask_b32_e64 v11, v8, v10, s[76:77]
	v_cndmask_b32_e64 v13, v14, v12, s[76:77]
	v_cndmask_b32_e64 v15, v12, v14, s[76:77]
	v_cndmask_b32_e64 v17, v18, v16, s[76:77]
	v_cndmask_b32_e64 v19, v16, v18, s[76:77]
	v_cndmask_b32_e64 v21, v22, v20, s[76:77]
	v_cndmask_b32_e64 v23, v20, v22, s[76:77]
	v_cndmask_b32_e64 v25, v26, v24, s[76:77]
	v_cndmask_b32_e64 v27, v24, v26, s[76:77]
	v_cndmask_b32_e64 v29, v30, v28, s[76:77]
	v_cndmask_b32_e64 v31, v28, v30, s[76:77]
	v_cndmask_b32_e64 v33, v34, v32, s[76:77]
	v_cndmask_b32_e64 v35, v32, v34, s[76:77]
	v_mov_b32_dpp v4, v5 row_ror:8 row_mask:0xf bank_mask:0xf
	v_mov_b32_dpp v8, v9 row_ror:8 row_mask:0xf bank_mask:0xf
	v_mov_b32_dpp v12, v13 row_ror:8 row_mask:0xf bank_mask:0xf
	v_mov_b32_dpp v16, v17 row_ror:8 row_mask:0xf bank_mask:0xf
	v_mov_b32_dpp v20, v21 row_ror:8 row_mask:0xf bank_mask:0xf
	v_mov_b32_dpp v24, v25 row_ror:8 row_mask:0xf bank_mask:0xf
	v_mov_b32_dpp v28, v29 row_ror:8 row_mask:0xf bank_mask:0xf
	v_mov_b32_dpp v32, v33 row_ror:8 row_mask:0xf bank_mask:0xf
	s_nop 1
	v_perm_b32 v68, v7, v4, v104
	v_perm_b32 v69, v7, v4, v105
	v_perm_b32 v70, v11, v8, v104
	v_perm_b32 v71, v11, v8, v105
	v_perm_b32 v72, v15, v12, v104
	v_perm_b32 v73, v15, v12, v105
	v_perm_b32 v74, v19, v16, v104
	v_perm_b32 v75, v19, v16, v105
	v_perm_b32 v76, v23, v20, v104
	v_perm_b32 v77, v23, v20, v105
	v_perm_b32 v78, v27, v24, v104
	v_perm_b32 v79, v27, v24, v105
	v_perm_b32 v80, v31, v28, v104
	v_perm_b32 v81, v31, v28, v105
	v_perm_b32 v82, v35, v32, v104
	v_perm_b32 v83, v35, v32, v105
	s_mov_b64 s[72:73], s[66:67]
	s_mov_b32 s74, 0
	s_cmp_ge_u32 s52, s32
	s_cbranch_scc1 .Ldt2_nlA
	s_cmpk_ge_u32 s52, 0x1410
	s_cbranch_scc1 .Ldt2_out2
	s_sub_i32 s0, s52, 0xa08
	s_mul_i32 s1, s0, 0xcc3
	s_lshr_b32 s1, s1, 20
	s_mul_i32 s16, s1, 0x141
	s_sub_u32 s16, s0, s16
	s_lshl_b32 s17, s16, 7
	s_mul_i32 s20, s1, 0x1410000
	s_add_u32 s17, s17, s20
	s_add_u32 s64, s54, s17
	s_addc_u32 s65, s55, 0
	s_mov_b32 s25, 0xa080
	s_lshl_b32 s20, s1, 10
	s_cmpk_lt_u32 s16, 0x80
	s_cbranch_scc1 .Ldt2_wlo2
	s_cmpk_eq_u32 s16, 0x80
	s_cbranch_scc1 .Ldt2_wlr2
	s_add_i32 s16, s16, -1

.Ldt2_ud2:
	v_mul_u32_u24_e32 v96, s25, v93
	s_lshl_b32 s24, s25, 6
	v_add_u32_e32 v96, v96, v94
	v_add_u32_e32 v97, s24, v96
	v_add_u32_e32 v98, s24, v97
	v_add_u32_e32 v99, s24, v98
	v_add_u32_e32 v100, s24, v99
	v_add_u32_e32 v101, s24, v100
	v_add_u32_e32 v102, s24, v101
	v_add_u32_e32 v103, s24, v102
	global_load_dwordx4 v[4:7], v96, s[64:65] nt
	global_load_dwordx4 v[8:11], v97, s[64:65] nt
	global_load_dwordx4 v[12:15], v98, s[64:65] nt
	global_load_dwordx4 v[16:19], v99, s[64:65] nt
	global_load_dwordx4 v[20:23], v100, s[64:65] nt
	global_load_dwordx4 v[24:27], v101, s[64:65] nt
	global_load_dwordx4 v[28:31], v102, s[64:65] nt
	global_load_dwordx4 v[32:35], v103, s[64:65] nt
	s_mov_b32 s74, 1
	s_add_u32 s52, s52, s84
.Ldt2_nlA:
	ds_write_b32 v84, v68 offset:0
	ds_write_b32 v84, v69 offset:1040
	ds_write_b32 v84, v70 offset:128
	ds_write_b32 v84, v71 offset:1168
	ds_write_b32 v84, v72 offset:256
	ds_write_b32 v84, v73 offset:1296
	ds_write_b32 v84, v74 offset:384
	ds_write_b32 v84, v75 offset:1424
	ds_write_b32 v84, v76 offset:512
	ds_write_b32 v84, v77 offset:1552
	ds_write_b32 v84, v78 offset:640
	ds_write_b32 v84, v79 offset:1680
	ds_write_b32 v84, v80 offset:768
	ds_write_b32 v84, v81 offset:1808
	ds_write_b32 v84, v82 offset:896
	ds_write_b32 v84, v83 offset:1936
	s_waitcnt lgkmcnt(0)
	s_barrier
	ds_read_b128 v[68:71], v85 offset:0
	ds_read_b128 v[72:75], v86 offset:0
	ds_read_b128 v[76:79], v87 offset:0
	ds_read_b128 v[80:83], v88 offset:0
	s_waitcnt lgkmcnt(3)
	global_store_dwordx4 v89, v[68:71], s[72:73] nt
	s_waitcnt lgkmcnt(2)
	global_store_dwordx4 v90, v[72:75], s[72:73] nt
	s_waitcnt lgkmcnt(1)
	global_store_dwordx4 v91, v[76:79], s[72:73] nt
	s_waitcnt lgkmcnt(0)
	global_store_dwordx4 v92, v[80:83], s[72:73] nt
	s_add_u32 s53, s53, 1
	s_cmp_eq_u32 s75, 0
	s_cbranch_scc1 .Ldt2_end
.Ldt2_procB:
	s_cmp_eq_u32 s74, 0
	s_cbranch_scc1 .Ldt2_w0B
	s_cmp_lt_u32 s53, 2
	s_cbranch_scc1 .Ldt2_wsB
	s_waitcnt vmcnt(16)
	s_branch .Ldt2_wdB

.Ldt2_wdB:
	v_cvt_pk_bf16_f32 v36, v36, v37
	v_cvt_pk_bf16_f32 v38, v38, v39
	v_cvt_pk_bf16_f32 v40, v40, v41
	v_cvt_pk_bf16_f32 v42, v42, v43
	v_cvt_pk_bf16_f32 v44, v44, v45
	v_cvt_pk_bf16_f32 v46, v46, v47
	v_cvt_pk_bf16_f32 v48, v48, v49
	v_cvt_pk_bf16_f32 v50, v50, v51
	v_cvt_pk_bf16_f32 v52, v52, v53
	v_cvt_pk_bf16_f32 v54, v54, v55
	v_cvt_pk_bf16_f32 v56, v56, v57
	v_cvt_pk_bf16_f32 v58, v58, v59
	v_cvt_pk_bf16_f32 v60, v60, v61
	v_cvt_pk_bf16_f32 v62, v62, v63
	v_cvt_pk_bf16_f32 v64, v64, v65
	v_cvt_pk_bf16_f32 v66, v66, v67
	v_cndmask_b32_e64 v37, v38, v36, s[76:77]
	v_cndmask_b32_e64 v39, v36, v38, s[76:77]
	v_cndmask_b32_e64 v41, v42, v40, s[76:77]
	v_cndmask_b32_e64 v43, v40, v42, s[76:77]
	v_cndmask_b32_e64 v45, v46, v44, s[76:77]
	v_cndmask_b32_e64 v47, v44, v46, s[76:77]
	v_cndmask_b32_e64 v49, v50, v48, s[76:77]
	v_cndmask_b32_e64 v51, v48, v50, s[76:77]
	v_cndmask_b32_e64 v53, v54, v52, s[76:77]
	v_cndmask_b32_e64 v55, v52, v54, s[76:77]
	v_cndmask_b32_e64 v57, v58, v56, s[76:77]
	v_cndmask_b32_e64 v59, v56, v58, s[76:77]
	v_cndmask_b32_e64 v61, v62, v60, s[76:77]
	v_cndmask_b32_e64 v63, v60, v62, s[76:77]
	v_cndmask_b32_e64 v65, v66, v64, s[76:77]
	v_cndmask_b32_e64 v67, v64, v66, s[76:77]
	v_mov_b32_dpp v36, v37 row_ror:8 row_mask:0xf bank_mask:0xf
	v_mov_b32_dpp v40, v41 row_ror:8 row_mask:0xf bank_mask:0xf
	v_mov_b32_dpp v44, v45 row_ror:8 row_mask:0xf bank_mask:0xf
	v_mov_b32_dpp v48, v49 row_ror:8 row_mask:0xf bank_mask:0xf
	v_mov_b32_dpp v52, v53 row_ror:8 row_mask:0xf bank_mask:0xf
	v_mov_b32_dpp v56, v57 row_ror:8 row_mask:0xf bank_mask:0xf
	v_mov_b32_dpp v60, v61 row_ror:8 row_mask:0xf bank_mask:0xf
	v_mov_b32_dpp v64, v65 row_ror:8 row_mask:0xf bank_mask:0xf
	s_nop 1
	v_perm_b32 v68, v39, v36, v104
	v_perm_b32 v69, v39, v36, v105
	v_perm_b32 v70, v43, v40, v104
	v_perm_b32 v71, v43, v40, v105
	v_perm_b32 v72, v47, v44, v104
	v_perm_b32 v73, v47, v44, v105
	v_perm_b32 v74, v51, v48, v104
	v_perm_b32 v75, v51, v48, v105
	v_perm_b32 v76, v55, v52, v104
	v_perm_b32 v77, v55, v52, v105
	v_perm_b32 v78, v59, v56, v104
	v_perm_b32 v79, v59, v56, v105
	v_perm_b32 v80, v63, v60, v104
	v_perm_b32 v81, v63, v60, v105
	v_perm_b32 v82, v67, v64, v104
	v_perm_b32 v83, v67, v64, v105
	s_mov_b64 s[72:73], s[34:35]
	s_mov_b32 s75, 0
	s_cmp_ge_u32 s52, s32
	s_cbranch_scc1 .Ldt2_nlB
	s_cmpk_ge_u32 s52, 0x1410
	s_cbranch_scc1 .Ldt2_out3
	s_sub_i32 s0, s52, 0xa08
	s_mul_i32 s1, s0, 0xcc3
	s_lshr_b32 s1, s1, 20
	s_mul_i32 s16, s1, 0x141
	s_sub_u32 s16, s0, s16
	s_lshl_b32 s17, s16, 7
	s_mul_i32 s20, s1, 0x1410000
	s_add_u32 s17, s17, s20
	s_add_u32 s70, s54, s17
	s_addc_u32 s71, s55, 0
	s_mov_b32 s25, 0xa080
	s_lshl_b32 s20, s1, 10
	s_cmpk_lt_u32 s16, 0x80
	s_cbranch_scc1 .Ldt2_wlo3
	s_cmpk_eq_u32 s16, 0x80
	s_cbranch_scc1 .Ldt2_wlr3
	s_add_i32 s16, s16, -1

.Ldt2_nlB:
	ds_write_b32 v84, v68 offset:33280
	ds_write_b32 v84, v69 offset:34320
	ds_write_b32 v84, v70 offset:33408
	ds_write_b32 v84, v71 offset:34448
	ds_write_b32 v84, v72 offset:33536
	ds_write_b32 v84, v73 offset:34576
	ds_write_b32 v84, v74 offset:33664
	ds_write_b32 v84, v75 offset:34704
	ds_write_b32 v84, v76 offset:33792
	ds_write_b32 v84, v77 offset:34832
	ds_write_b32 v84, v78 offset:33920
	ds_write_b32 v84, v79 offset:34960
	ds_write_b32 v84, v80 offset:34048
	ds_write_b32 v84, v81 offset:35088
	ds_write_b32 v84, v82 offset:34176
	ds_write_b32 v84, v83 offset:35216
	s_waitcnt lgkmcnt(0)
	s_barrier
	ds_read_b128 v[68:71], v85 offset:33280
	ds_read_b128 v[72:75], v86 offset:33280
	ds_read_b128 v[76:79], v87 offset:33280
	ds_read_b128 v[80:83], v88 offset:33280
	s_waitcnt lgkmcnt(3)
	global_store_dwordx4 v89, v[68:71], s[72:73] nt
	s_waitcnt lgkmcnt(2)
	global_store_dwordx4 v90, v[72:75], s[72:73] nt
	s_waitcnt lgkmcnt(1)
	global_store_dwordx4 v91, v[76:79], s[72:73] nt
	s_waitcnt lgkmcnt(0)
	global_store_dwordx4 v92, v[80:83], s[72:73] nt
	s_add_u32 s53, s53, 1
	s_cmp_eq_u32 s74, 0
	s_cbranch_scc0 .Ldt2_procA
.Ldt2_end:
	s_nop 1
	s_waitcnt lgkmcnt(0)
	s_barrier
.Ldt2_skip:
	s_ashr_i32 s0, s87, 31
	s_lshr_b32 s0, s0, 29
	s_add_i32 s0, s87, s0
	s_ashr_i32 s1, s0, 3
	s_and_b32 s0, s0, -8
	s_sub_i32 s0, s87, s0
	s_cmp_lt_i32 s0, 0
	s_movk_i32 s16, 0xa1
	s_cselect_b32 s16, s16, 0xa0
	s_mul_i32 s0, s16, s0
	v_mov_b32_e32 v16, v180
	s_add_i32 s0, s0, s1
	s_mul_hi_i32 s1, s0, 0x66666667
	v_ashrrev_i32_e32 v0, 31, v16
	v_lshrrev_b32_e32 v0, 26, v0
	s_lshr_b32 s16, s1, 31
	s_ashr_i32 s1, s1, 7
	v_add_u32_e32 v0, v16, v0
	s_add_i32 s20, s1, s16
	v_ashrrev_i32_e32 v1, 6, v0
	v_bfe_i32 v0, v16, 27, 1
	s_mul_i32 s1, s20, 0x140
	v_lshlrev_b32_e32 v17, 4, v16
	v_lshrrev_b32_e32 v0, 22, v0
	s_sub_i32 s0, s0, s1
	v_add_u32_e32 v0, v17, v0
	s_sext_i32_i16 s1, s0
	v_and_b32_e32 v0, 0xfffffc00, v0
	s_bfe_u32 s1, s1, 0x3001c
	v_sub_u32_e32 v0, v17, v0
	s_add_i32 s1, s0, s1
	v_lshrrev_b32_e32 v2, 4, v0
	s_sext_i32_i16 s16, s1
	s_and_b32 s1, s1, 0xfff8
	v_bitop3_b32 v2, v2, v0, 32 bitop3:0x6c
	s_sub_i32 s0, s0, s1
	v_ashrrev_i32_e32 v3, 31, v2
	s_sext_i32_i16 s0, s0
	v_lshrrev_b32_e32 v3, 26, v3
	s_lshl_b32 s21, s0, 8
	s_lshl_b32 s0, s16, 5
	v_add_u32_e32 v3, v2, v3
	s_and_b32 s0, s0, 0xffffff00
	v_lshlrev_b32_e32 v0, 3, v1
	v_ashrrev_i32_e32 v4, 6, v3
	v_and_b32_e32 v3, 0xc0, v3
	s_ashr_i32 s1, s0, 31
	v_readlane_b32 s52, v254, 60
	v_and_b32_e32 v0, -16, v0
	v_lshlrev_b32_e32 v1, 5, v1
	v_sub_u32_e32 v2, v2, v3
	s_lshl_b64 s[24:25], s[0:1], 13
	v_readlane_b32 s64, v253, 8
	v_add_u32_e32 v0, v4, v0
	v_and_b32_e32 v1, 32, v1
	v_ashrrev_i16_sdwa v2, v145, sext(v2) dst_sel:DWORD dst_unused:UNUSED_PAD src0_sel:DWORD src1_sel:BYTE_0
	v_readlane_b32 s65, v253, 9
	s_add_u32 s16, s64, s24
	v_add_u32_sdwa v128, v1, sext(v2) dst_sel:DWORD dst_unused:UNUSED_PAD src0_sel:DWORD src1_sel:WORD_0
	v_ashrrev_i32_e32 v1, 31, v0
	s_addc_u32 s17, s65, s25
	v_lshlrev_b64 v[130:131], 13, v[0:1]
	v_ashrrev_i32_e32 v129, 31, v128
	v_lshl_add_u64 v[2:3], s[16:17], 0, v[130:131]
	v_lshlrev_b64 v[0:1], 1, v[128:129]
	v_add_u32_e32 v18, 0x2000, v17
	v_lshl_add_u64 v[4:5], v[2:3], 0, v[0:1]
	v_ashrrev_i32_e32 v2, 31, v18
	v_lshrrev_b32_e32 v2, 22, v2
	v_add_u32_e32 v2, v18, v2
	v_ashrrev_i32_e32 v3, 10, v2
	v_mul_i32_i24_e32 v2, 0x400, v3
	v_sub_u32_e32 v2, v18, v2
	v_lshrrev_b32_e32 v6, 4, v2
	v_bitop3_b32 v6, v6, v2, 32 bitop3:0x6c
	v_ashrrev_i32_e32 v7, 31, v6
	v_lshrrev_b32_e32 v7, 26, v7
	v_add_u32_e32 v7, v6, v7
	v_lshlrev_b32_e32 v2, 3, v3
	v_ashrrev_i32_e32 v8, 6, v7
	v_and_b32_e32 v7, 0xc0, v7
	v_add_u32_e32 v146, s33, v17
	v_and_b32_e32 v2, -16, v2
	v_lshlrev_b32_e32 v3, 5, v3
	v_sub_u32_e32 v6, v6, v7
	v_readfirstlane_b32 s1, v146
	v_add_u32_e32 v2, v8, v2
	v_and_b32_e32 v3, 32, v3
	v_ashrrev_i16_sdwa v6, v145, sext(v6) dst_sel:DWORD dst_unused:UNUSED_PAD src0_sel:DWORD src1_sel:BYTE_0
	v_add_u32_e32 v8, s33, v18
	s_mov_b32 m0, s1
	v_add_u32_sdwa v132, v3, sext(v6) dst_sel:DWORD dst_unused:UNUSED_PAD src0_sel:DWORD src1_sel:WORD_0
	v_ashrrev_i32_e32 v3, 31, v2
	v_readfirstlane_b32 s1, v8
	global_load_lds_dwordx4 v[4:5], off
	v_lshlrev_b64 v[134:135], 13, v[2:3]
	s_mov_b32 m0, s1
	s_lshl_b32 s1, s20, 11
	v_lshl_add_u64 v[6:7], s[16:17], 0, v[134:135]
	s_add_i32 s16, s21, s1
	s_ashr_i32 s17, s16, 31
	s_lshl_b64 s[34:35], s[16:17], 13
	v_ashrrev_i32_e32 v133, 31, v132
	s_add_u32 s20, s68, s34
	v_lshlrev_b64 v[2:3], 1, v[132:133]
	s_addc_u32 s21, s69, s35
	v_add_u32_e32 v148, 0, v17
	v_lshl_add_u64 v[6:7], v[6:7], 0, v[2:3]
	v_lshl_add_u64 v[8:9], s[20:21], 0, v[130:131]
	v_readfirstlane_b32 s1, v148
	v_lshl_add_u64 v[10:11], s[20:21], 0, v[134:135]
	v_add_u32_e32 v149, 0x2000, v148
	s_or_b32 s20, s0, 0x80
	v_readfirstlane_b32 s88, v16
	global_load_lds_dwordx4 v[6:7], off
	v_lshl_add_u64 v[8:9], v[8:9], 0, v[0:1]
	s_mov_b32 m0, s1
	v_readfirstlane_b32 s1, v149
	s_ashr_i32 s21, s20, 31
	global_load_lds_dwordx4 v[8:9], off
	s_mov_b32 m0, s1
	s_ashr_i32 s1, s88, 8
	s_lshl_b64 s[20:21], s[20:21], 13
	s_add_u32 s20, s64, s20
	s_addc_u32 s21, s65, s21
	v_lshl_add_u64 v[12:13], s[20:21], 0, v[130:131]
	v_lshl_add_u64 v[14:15], s[20:21], 0, v[134:135]
	s_or_b32 s20, s16, 0x80
	s_ashr_i32 s21, s20, 31
	v_add_u32_e32 v151, s80, v17
	s_lshl_b64 s[20:21], s[20:21], 13
	v_lshl_add_u64 v[10:11], v[10:11], 0, v[2:3]
	v_readfirstlane_b32 s17, v151
	v_add_u32_e32 v18, s80, v18
	s_add_u32 s20, s68, s20
	global_load_lds_dwordx4 v[10:11], off
	v_lshl_add_u64 v[12:13], v[12:13], 0, v[0:1]
	s_mov_b32 m0, s17
	v_readfirstlane_b32 s17, v18
	s_addc_u32 s21, s69, s21
	v_add_u32_e32 v153, 0x4000, v148
	global_load_lds_dwordx4 v[12:13], off
	v_lshl_add_u64 v[14:15], v[14:15], 0, v[2:3]
	s_mov_b32 m0, s17
	v_lshl_add_u64 v[18:19], s[20:21], 0, v[130:131]
	v_readfirstlane_b32 s17, v153
	global_load_lds_dwordx4 v[14:15], off
	v_lshl_add_u64 v[18:19], v[18:19], 0, v[0:1]
	s_mov_b32 m0, s17
	v_add_u32_e32 v154, 0x6000, v148
	global_load_lds_dwordx4 v[18:19], off
	v_lshl_add_u64 v[18:19], s[20:21], 0, v[134:135]
	v_readfirstlane_b32 s17, v154
	v_lshl_add_u64 v[18:19], v[18:19], 0, v[2:3]
	s_mov_b32 m0, s17
	s_cmp_lg_u32 s1, 1
	global_load_lds_dwordx4 v[18:19], off
	v_readlane_b32 s53, v254, 61
	v_readlane_b32 s54, v254, 62
	v_readlane_b32 s55, v254, 63
	v_readlane_b32 s56, v253, 0
	v_readlane_b32 s57, v253, 1
	v_readlane_b32 s58, v253, 2
	v_readlane_b32 s59, v253, 3
	v_readlane_b32 s60, v253, 4
	v_readlane_b32 s61, v253, 5
	v_readlane_b32 s62, v253, 6
	v_readlane_b32 s63, v253, 7
	v_readlane_b32 s66, v253, 10
	v_readlane_b32 s67, v253, 11
	s_cbranch_scc1 .LBB0_223
	s_barrier
